# vk fronts the first operand load; nops front the others; tw between the first two DPP stages
# speedup vs baseline: 1.0110x; 1.0022x over previous
.LBB0_682:
	s_bitcmp1_b32 s30, 0
	s_cselect_b32 s6, 0xe000, 0
	s_add_i32 s6, s6, 0
	v_add_u32_e32 v90, s6, v58
	v_sub_u32_e32 v88, v90, v61
	v_add_u32_e32 v89, s6, v86
	ds_read_b128 v[4:7], v90 offset:0x4000
	ds_read_b128 v[8:11], v90 offset:0x0
	ds_read2st64_b32 v[108:109], v89 offset0:192 offset1:193
	ds_read2st64_b64 v[100:103], v88 offset0:64 offset1:65
	ds_read_b128 v[112:115], v90 offset:0x4200
	ds_read_b128 v[96:99], v90 offset:0x200
	ds_read_b128 v[120:123], v90 offset:0x4400
	ds_read_b128 v[124:127], v90 offset:0x400
	v_mov_b32_e32 v93, v91
	s_waitcnt lgkmcnt(5)
	v_pk_mul_f32 v[0:1], v[52:53], v[4:5] op_sel_hi:[0,1]
	v_pk_fma_f32 v[0:1], v[52:53], v[6:7], v[0:1] op_sel:[1,0,0]
	v_pk_mul_f32 v[10:11], v[108:109], v[10:11] op_sel_hi:[0,1]
	ds_read_b128 v[4:7], v90 offset:0x4600
	v_add_f32_dpp v0, v0, v0 quad_perm:[1,0,3,2] row_mask:0xf bank_mask:0xf bound_ctrl:1
	v_add_f32_dpp v1, v1, v1 quad_perm:[1,0,3,2] row_mask:0xf bank_mask:0xf bound_ctrl:1
	v_pk_fma_f32 v[54:55], v[52:53], v[8:9], v[10:11]
	v_add_f32_dpp v0, v0, v0 quad_perm:[2,3,0,1] row_mask:0xf bank_mask:0xf bound_ctrl:1
	s_nop 0
	ds_read_b128 v[8:11], v90 offset:0x600
	v_add_f32_dpp v0, v0, v0 row_half_mirror row_mask:0xf bank_mask:0xf bound_ctrl:1
	s_nop 0
	ds_read2st64_b32 v[110:111], v89 offset0:194 offset1:195
	ds_read2st64_b64 v[104:107], v88 offset0:66 offset1:67
	v_add_f32_dpp v2, v0, v0 row_mirror row_mask:0xf bank_mask:0xf bound_ctrl:1
	v_add_f32_dpp v0, v0, v0 row_mirror row_mask:0xf bank_mask:0xf bound_ctrl:1
	s_nop 0
	s_waitcnt lgkmcnt(6)
	v_permlane16_swap_b32_e32 v0, v2
	v_add_f32_e32 v0, v0, v2
	v_pk_fma_f32 v[52:53], v[100:101], v[0:1], v[54:55] op_sel_hi:[1,0,1]
	v_pk_mul_f32 v[118:119], v[52:53], v[112:113] op_sel_hi:[0,1]
	v_pk_fma_f32 v[118:119], v[52:53], v[114:115], v[118:119] op_sel:[1,0,0]
	v_pk_mul_f32 v[98:99], v[108:109], v[98:99] op_sel:[1,0]
	ds_read_b128 v[112:115], v90 offset:0x4800
	v_add_f32_dpp v118, v118, v118 quad_perm:[1,0,3,2] row_mask:0xf bank_mask:0xf bound_ctrl:1
	v_add_f32_dpp v119, v119, v119 quad_perm:[1,0,3,2] row_mask:0xf bank_mask:0xf bound_ctrl:1
	v_pk_fma_f32 v[54:55], v[52:53], v[96:97], v[98:99]
	v_add_f32_dpp v118, v118, v118 quad_perm:[2,3,0,1] row_mask:0xf bank_mask:0xf bound_ctrl:1
	s_nop 0
	ds_read_b128 v[96:99], v90 offset:0x800
	v_add_f32_dpp v118, v118, v118 row_half_mirror row_mask:0xf bank_mask:0xf bound_ctrl:1
	s_nop 0
	ds_write2_b32 v93, v1, v119 offset0:0 offset1:36
	v_add_f32_dpp v2, v118, v118 row_mirror row_mask:0xf bank_mask:0xf bound_ctrl:1
	v_add_f32_dpp v118, v118, v118 row_mirror row_mask:0xf bank_mask:0xf bound_ctrl:1
	s_nop 0
	s_waitcnt lgkmcnt(4)
	v_permlane16_swap_b32_e32 v118, v2
	v_add_f32_e32 v118, v118, v2
	v_pk_fma_f32 v[52:53], v[102:103], v[118:119], v[54:55] op_sel_hi:[1,0,1]
	v_pk_mul_f32 v[0:1], v[52:53], v[120:121] op_sel_hi:[0,1]
	v_pk_fma_f32 v[0:1], v[52:53], v[122:123], v[0:1] op_sel:[1,0,0]
	v_pk_mul_f32 v[126:127], v[110:111], v[126:127] op_sel_hi:[0,1]
	ds_read_b128 v[120:123], v90 offset:0x4a00
	v_add_f32_dpp v0, v0, v0 quad_perm:[1,0,3,2] row_mask:0xf bank_mask:0xf bound_ctrl:1
	v_add_f32_dpp v1, v1, v1 quad_perm:[1,0,3,2] row_mask:0xf bank_mask:0xf bound_ctrl:1
	v_pk_fma_f32 v[54:55], v[52:53], v[124:125], v[126:127]
	v_add_f32_dpp v0, v0, v0 quad_perm:[2,3,0,1] row_mask:0xf bank_mask:0xf bound_ctrl:1
	s_nop 0
	ds_read_b128 v[124:127], v90 offset:0xa00
	v_add_f32_dpp v0, v0, v0 row_half_mirror row_mask:0xf bank_mask:0xf bound_ctrl:1
	s_nop 0
	ds_read2st64_b32 v[108:109], v89 offset0:196 offset1:197
	ds_read2st64_b64 v[100:103], v88 offset0:68 offset1:69
	v_add_f32_dpp v2, v0, v0 row_mirror row_mask:0xf bank_mask:0xf bound_ctrl:1
	v_add_f32_dpp v0, v0, v0 row_mirror row_mask:0xf bank_mask:0xf bound_ctrl:1
	s_nop 0
	s_waitcnt lgkmcnt(7)
	v_permlane16_swap_b32_e32 v0, v2
	v_add_f32_e32 v0, v0, v2
	v_pk_fma_f32 v[52:53], v[104:105], v[0:1], v[54:55] op_sel_hi:[1,0,1]
	v_pk_mul_f32 v[118:119], v[52:53], v[4:5] op_sel_hi:[0,1]
	v_pk_fma_f32 v[118:119], v[52:53], v[6:7], v[118:119] op_sel:[1,0,0]
	v_pk_mul_f32 v[10:11], v[110:111], v[10:11] op_sel:[1,0]
	ds_read_b128 v[4:7], v90 offset:0x4c00
	v_add_f32_dpp v118, v118, v118 quad_perm:[1,0,3,2] row_mask:0xf bank_mask:0xf bound_ctrl:1
	v_add_f32_dpp v119, v119, v119 quad_perm:[1,0,3,2] row_mask:0xf bank_mask:0xf bound_ctrl:1
	v_pk_fma_f32 v[54:55], v[52:53], v[8:9], v[10:11]
	v_add_f32_dpp v118, v118, v118 quad_perm:[2,3,0,1] row_mask:0xf bank_mask:0xf bound_ctrl:1
	s_nop 0
	ds_read_b128 v[8:11], v90 offset:0xc00
	v_add_f32_dpp v118, v118, v118 row_half_mirror row_mask:0xf bank_mask:0xf bound_ctrl:1
	s_nop 0
	ds_write2_b32 v93, v1, v119 offset0:72 offset1:108
	v_add_f32_dpp v2, v118, v118 row_mirror row_mask:0xf bank_mask:0xf bound_ctrl:1
	v_add_f32_dpp v118, v118, v118 row_mirror row_mask:0xf bank_mask:0xf bound_ctrl:1
	s_nop 0
	s_waitcnt lgkmcnt(4)
	v_permlane16_swap_b32_e32 v118, v2
	v_add_f32_e32 v118, v118, v2
	v_pk_fma_f32 v[52:53], v[106:107], v[118:119], v[54:55] op_sel_hi:[1,0,1]
	v_pk_mul_f32 v[0:1], v[52:53], v[112:113] op_sel_hi:[0,1]
	v_pk_fma_f32 v[0:1], v[52:53], v[114:115], v[0:1] op_sel:[1,0,0]
	v_pk_mul_f32 v[98:99], v[108:109], v[98:99] op_sel_hi:[0,1]
	ds_read_b128 v[112:115], v90 offset:0x4e00
	v_add_f32_dpp v0, v0, v0 quad_perm:[1,0,3,2] row_mask:0xf bank_mask:0xf bound_ctrl:1
	v_add_f32_dpp v1, v1, v1 quad_perm:[1,0,3,2] row_mask:0xf bank_mask:0xf bound_ctrl:1
	v_pk_fma_f32 v[54:55], v[52:53], v[96:97], v[98:99]
	v_add_f32_dpp v0, v0, v0 quad_perm:[2,3,0,1] row_mask:0xf bank_mask:0xf bound_ctrl:1
	s_nop 0
	ds_read_b128 v[96:99], v90 offset:0xe00
	v_add_f32_dpp v0, v0, v0 row_half_mirror row_mask:0xf bank_mask:0xf bound_ctrl:1
	s_nop 0
	ds_read2st64_b32 v[110:111], v89 offset0:198 offset1:199
	ds_read2st64_b64 v[104:107], v88 offset0:70 offset1:71
	v_add_f32_dpp v2, v0, v0 row_mirror row_mask:0xf bank_mask:0xf bound_ctrl:1
	v_add_f32_dpp v0, v0, v0 row_mirror row_mask:0xf bank_mask:0xf bound_ctrl:1
	s_nop 0
	s_waitcnt lgkmcnt(7)
	v_permlane16_swap_b32_e32 v0, v2
	v_add_f32_e32 v0, v0, v2
	v_pk_fma_f32 v[52:53], v[100:101], v[0:1], v[54:55] op_sel_hi:[1,0,1]
	v_pk_mul_f32 v[118:119], v[52:53], v[120:121] op_sel_hi:[0,1]
	v_pk_fma_f32 v[118:119], v[52:53], v[122:123], v[118:119] op_sel:[1,0,0]
	v_pk_mul_f32 v[126:127], v[108:109], v[126:127] op_sel:[1,0]
	ds_read_b128 v[120:123], v90 offset:0x5000
	v_add_f32_dpp v118, v118, v118 quad_perm:[1,0,3,2] row_mask:0xf bank_mask:0xf bound_ctrl:1
	v_add_f32_dpp v119, v119, v119 quad_perm:[1,0,3,2] row_mask:0xf bank_mask:0xf bound_ctrl:1
	v_pk_fma_f32 v[54:55], v[52:53], v[124:125], v[126:127]
	v_add_f32_dpp v118, v118, v118 quad_perm:[2,3,0,1] row_mask:0xf bank_mask:0xf bound_ctrl:1
	s_nop 0
	ds_read_b128 v[124:127], v90 offset:0x1000
	v_add_f32_dpp v118, v118, v118 row_half_mirror row_mask:0xf bank_mask:0xf bound_ctrl:1
	s_nop 0
	ds_write2_b32 v93, v1, v119 offset0:144 offset1:180
	v_add_f32_dpp v2, v118, v118 row_mirror row_mask:0xf bank_mask:0xf bound_ctrl:1
	v_add_f32_dpp v118, v118, v118 row_mirror row_mask:0xf bank_mask:0xf bound_ctrl:1
	s_nop 0
	s_waitcnt lgkmcnt(4)
	v_permlane16_swap_b32_e32 v118, v2
	v_add_f32_e32 v118, v118, v2
	v_pk_fma_f32 v[52:53], v[102:103], v[118:119], v[54:55] op_sel_hi:[1,0,1]
	v_pk_mul_f32 v[0:1], v[52:53], v[4:5] op_sel_hi:[0,1]
	v_pk_fma_f32 v[0:1], v[52:53], v[6:7], v[0:1] op_sel:[1,0,0]
	v_pk_mul_f32 v[10:11], v[110:111], v[10:11] op_sel_hi:[0,1]
	ds_read_b128 v[4:7], v90 offset:0x5200
	v_add_f32_dpp v0, v0, v0 quad_perm:[1,0,3,2] row_mask:0xf bank_mask:0xf bound_ctrl:1
	v_add_f32_dpp v1, v1, v1 quad_perm:[1,0,3,2] row_mask:0xf bank_mask:0xf bound_ctrl:1
	v_pk_fma_f32 v[54:55], v[52:53], v[8:9], v[10:11]
	v_add_f32_dpp v0, v0, v0 quad_perm:[2,3,0,1] row_mask:0xf bank_mask:0xf bound_ctrl:1
	s_nop 0
	ds_read_b128 v[8:11], v90 offset:0x1200
	v_add_f32_dpp v0, v0, v0 row_half_mirror row_mask:0xf bank_mask:0xf bound_ctrl:1
	s_nop 0
	ds_read2st64_b32 v[108:109], v89 offset0:200 offset1:201
	ds_read2st64_b64 v[100:103], v88 offset0:72 offset1:73
	v_add_f32_dpp v2, v0, v0 row_mirror row_mask:0xf bank_mask:0xf bound_ctrl:1
	v_add_f32_dpp v0, v0, v0 row_mirror row_mask:0xf bank_mask:0xf bound_ctrl:1
	s_nop 0
	s_waitcnt lgkmcnt(7)
	v_permlane16_swap_b32_e32 v0, v2
	v_add_f32_e32 v0, v0, v2
	v_pk_fma_f32 v[52:53], v[104:105], v[0:1], v[54:55] op_sel_hi:[1,0,1]
	v_pk_mul_f32 v[118:119], v[52:53], v[112:113] op_sel_hi:[0,1]
	v_pk_fma_f32 v[118:119], v[52:53], v[114:115], v[118:119] op_sel:[1,0,0]
	v_pk_mul_f32 v[98:99], v[110:111], v[98:99] op_sel:[1,0]
	ds_read_b128 v[112:115], v90 offset:0x5400
	v_add_f32_dpp v118, v118, v118 quad_perm:[1,0,3,2] row_mask:0xf bank_mask:0xf bound_ctrl:1
	v_add_f32_dpp v119, v119, v119 quad_perm:[1,0,3,2] row_mask:0xf bank_mask:0xf bound_ctrl:1
	v_pk_fma_f32 v[54:55], v[52:53], v[96:97], v[98:99]
	v_add_f32_dpp v118, v118, v118 quad_perm:[2,3,0,1] row_mask:0xf bank_mask:0xf bound_ctrl:1
	s_nop 0
	ds_read_b128 v[96:99], v90 offset:0x1400
	v_add_f32_dpp v118, v118, v118 row_half_mirror row_mask:0xf bank_mask:0xf bound_ctrl:1
	s_nop 0
	ds_write2_b32 v93, v1, v119 offset0:216 offset1:252
	v_add_f32_dpp v2, v118, v118 row_mirror row_mask:0xf bank_mask:0xf bound_ctrl:1
	v_add_f32_dpp v118, v118, v118 row_mirror row_mask:0xf bank_mask:0xf bound_ctrl:1
	s_nop 0
	s_waitcnt lgkmcnt(4)
	v_permlane16_swap_b32_e32 v118, v2
	v_add_f32_e32 v118, v118, v2
	v_pk_fma_f32 v[52:53], v[106:107], v[118:119], v[54:55] op_sel_hi:[1,0,1]
	v_pk_mul_f32 v[0:1], v[52:53], v[120:121] op_sel_hi:[0,1]
	v_pk_fma_f32 v[0:1], v[52:53], v[122:123], v[0:1] op_sel:[1,0,0]
	v_pk_mul_f32 v[126:127], v[108:109], v[126:127] op_sel_hi:[0,1]
	ds_read_b128 v[120:123], v90 offset:0x5600
	v_add_f32_dpp v0, v0, v0 quad_perm:[1,0,3,2] row_mask:0xf bank_mask:0xf bound_ctrl:1
	v_add_f32_dpp v1, v1, v1 quad_perm:[1,0,3,2] row_mask:0xf bank_mask:0xf bound_ctrl:1
	v_pk_fma_f32 v[54:55], v[52:53], v[124:125], v[126:127]
	v_add_f32_dpp v0, v0, v0 quad_perm:[2,3,0,1] row_mask:0xf bank_mask:0xf bound_ctrl:1
	s_nop 0
	ds_read_b128 v[124:127], v90 offset:0x1600
	v_add_f32_dpp v0, v0, v0 row_half_mirror row_mask:0xf bank_mask:0xf bound_ctrl:1
	s_nop 0
	ds_read2st64_b32 v[110:111], v89 offset0:202 offset1:203
	ds_read2st64_b64 v[104:107], v88 offset0:74 offset1:75
	v_add_f32_dpp v2, v0, v0 row_mirror row_mask:0xf bank_mask:0xf bound_ctrl:1
	v_add_f32_dpp v0, v0, v0 row_mirror row_mask:0xf bank_mask:0xf bound_ctrl:1
	v_add_u32_e32 v93, 0x480, v93
	s_waitcnt lgkmcnt(7)
	v_permlane16_swap_b32_e32 v0, v2
	v_add_f32_e32 v0, v0, v2
	v_pk_fma_f32 v[52:53], v[100:101], v[0:1], v[54:55] op_sel_hi:[1,0,1]
	v_pk_mul_f32 v[118:119], v[52:53], v[4:5] op_sel_hi:[0,1]
	v_pk_fma_f32 v[118:119], v[52:53], v[6:7], v[118:119] op_sel:[1,0,0]
	v_pk_mul_f32 v[10:11], v[108:109], v[10:11] op_sel:[1,0]
	ds_read_b128 v[4:7], v90 offset:0x5800
	v_add_f32_dpp v118, v118, v118 quad_perm:[1,0,3,2] row_mask:0xf bank_mask:0xf bound_ctrl:1
	v_add_f32_dpp v119, v119, v119 quad_perm:[1,0,3,2] row_mask:0xf bank_mask:0xf bound_ctrl:1
	v_pk_fma_f32 v[54:55], v[52:53], v[8:9], v[10:11]
	v_add_f32_dpp v118, v118, v118 quad_perm:[2,3,0,1] row_mask:0xf bank_mask:0xf bound_ctrl:1
	s_nop 0
	ds_read_b128 v[8:11], v90 offset:0x1800
	v_add_f32_dpp v118, v118, v118 row_half_mirror row_mask:0xf bank_mask:0xf bound_ctrl:1
	s_nop 0
	ds_write2_b32 v93, v1, v119 offset0:0 offset1:36
	v_add_f32_dpp v2, v118, v118 row_mirror row_mask:0xf bank_mask:0xf bound_ctrl:1
	v_add_f32_dpp v118, v118, v118 row_mirror row_mask:0xf bank_mask:0xf bound_ctrl:1
	s_nop 0
	s_waitcnt lgkmcnt(4)
	v_permlane16_swap_b32_e32 v118, v2
	v_add_f32_e32 v118, v118, v2
	v_pk_fma_f32 v[52:53], v[102:103], v[118:119], v[54:55] op_sel_hi:[1,0,1]
	v_pk_mul_f32 v[0:1], v[52:53], v[112:113] op_sel_hi:[0,1]
	v_pk_fma_f32 v[0:1], v[52:53], v[114:115], v[0:1] op_sel:[1,0,0]
	v_pk_mul_f32 v[98:99], v[110:111], v[98:99] op_sel_hi:[0,1]
	ds_read_b128 v[112:115], v90 offset:0x5a00
	v_add_f32_dpp v0, v0, v0 quad_perm:[1,0,3,2] row_mask:0xf bank_mask:0xf bound_ctrl:1
	v_add_f32_dpp v1, v1, v1 quad_perm:[1,0,3,2] row_mask:0xf bank_mask:0xf bound_ctrl:1
	v_pk_fma_f32 v[54:55], v[52:53], v[96:97], v[98:99]
	v_add_f32_dpp v0, v0, v0 quad_perm:[2,3,0,1] row_mask:0xf bank_mask:0xf bound_ctrl:1
	s_nop 0
	ds_read_b128 v[96:99], v90 offset:0x1a00
	v_add_f32_dpp v0, v0, v0 row_half_mirror row_mask:0xf bank_mask:0xf bound_ctrl:1
	s_nop 0
	ds_read2st64_b32 v[108:109], v89 offset0:204 offset1:205
	ds_read2st64_b64 v[100:103], v88 offset0:76 offset1:77
	v_add_f32_dpp v2, v0, v0 row_mirror row_mask:0xf bank_mask:0xf bound_ctrl:1
	v_add_f32_dpp v0, v0, v0 row_mirror row_mask:0xf bank_mask:0xf bound_ctrl:1
	s_nop 0
	s_waitcnt lgkmcnt(7)
	v_permlane16_swap_b32_e32 v0, v2
	v_add_f32_e32 v0, v0, v2
	v_pk_fma_f32 v[52:53], v[104:105], v[0:1], v[54:55] op_sel_hi:[1,0,1]
	v_pk_mul_f32 v[118:119], v[52:53], v[120:121] op_sel_hi:[0,1]
	v_pk_fma_f32 v[118:119], v[52:53], v[122:123], v[118:119] op_sel:[1,0,0]
	v_pk_mul_f32 v[126:127], v[110:111], v[126:127] op_sel:[1,0]
	ds_read_b128 v[120:123], v90 offset:0x5c00
	v_add_f32_dpp v118, v118, v118 quad_perm:[1,0,3,2] row_mask:0xf bank_mask:0xf bound_ctrl:1
	v_add_f32_dpp v119, v119, v119 quad_perm:[1,0,3,2] row_mask:0xf bank_mask:0xf bound_ctrl:1
	v_pk_fma_f32 v[54:55], v[52:53], v[124:125], v[126:127]
	v_add_f32_dpp v118, v118, v118 quad_perm:[2,3,0,1] row_mask:0xf bank_mask:0xf bound_ctrl:1
	s_nop 0
	ds_read_b128 v[124:127], v90 offset:0x1c00
	v_add_f32_dpp v118, v118, v118 row_half_mirror row_mask:0xf bank_mask:0xf bound_ctrl:1
	s_nop 0
	ds_write2_b32 v93, v1, v119 offset0:72 offset1:108
	v_add_f32_dpp v2, v118, v118 row_mirror row_mask:0xf bank_mask:0xf bound_ctrl:1
	v_add_f32_dpp v118, v118, v118 row_mirror row_mask:0xf bank_mask:0xf bound_ctrl:1
	s_nop 0
	s_waitcnt lgkmcnt(4)
	v_permlane16_swap_b32_e32 v118, v2
	v_add_f32_e32 v118, v118, v2
	v_pk_fma_f32 v[52:53], v[106:107], v[118:119], v[54:55] op_sel_hi:[1,0,1]
	v_pk_mul_f32 v[0:1], v[52:53], v[4:5] op_sel_hi:[0,1]
	v_pk_fma_f32 v[0:1], v[52:53], v[6:7], v[0:1] op_sel:[1,0,0]
	v_pk_mul_f32 v[10:11], v[108:109], v[10:11] op_sel_hi:[0,1]
	ds_read_b128 v[4:7], v90 offset:0x5e00
	v_add_f32_dpp v0, v0, v0 quad_perm:[1,0,3,2] row_mask:0xf bank_mask:0xf bound_ctrl:1
	v_add_f32_dpp v1, v1, v1 quad_perm:[1,0,3,2] row_mask:0xf bank_mask:0xf bound_ctrl:1
	v_pk_fma_f32 v[54:55], v[52:53], v[8:9], v[10:11]
	v_add_f32_dpp v0, v0, v0 quad_perm:[2,3,0,1] row_mask:0xf bank_mask:0xf bound_ctrl:1
	s_nop 0
	ds_read_b128 v[8:11], v90 offset:0x1e00
	v_add_f32_dpp v0, v0, v0 row_half_mirror row_mask:0xf bank_mask:0xf bound_ctrl:1
	s_nop 0
	ds_read2st64_b32 v[110:111], v89 offset0:206 offset1:207
	ds_read2st64_b64 v[104:107], v88 offset0:78 offset1:79
	v_add_f32_dpp v2, v0, v0 row_mirror row_mask:0xf bank_mask:0xf bound_ctrl:1
	v_add_f32_dpp v0, v0, v0 row_mirror row_mask:0xf bank_mask:0xf bound_ctrl:1
	s_nop 0
	s_waitcnt lgkmcnt(7)
	v_permlane16_swap_b32_e32 v0, v2
	v_add_f32_e32 v0, v0, v2
	v_pk_fma_f32 v[52:53], v[100:101], v[0:1], v[54:55] op_sel_hi:[1,0,1]
	v_pk_mul_f32 v[118:119], v[52:53], v[112:113] op_sel_hi:[0,1]
	v_pk_fma_f32 v[118:119], v[52:53], v[114:115], v[118:119] op_sel:[1,0,0]
	v_pk_mul_f32 v[98:99], v[108:109], v[98:99] op_sel:[1,0]
	ds_read_b128 v[112:115], v90 offset:0x6000
	v_add_f32_dpp v118, v118, v118 quad_perm:[1,0,3,2] row_mask:0xf bank_mask:0xf bound_ctrl:1
	v_add_f32_dpp v119, v119, v119 quad_perm:[1,0,3,2] row_mask:0xf bank_mask:0xf bound_ctrl:1
	v_pk_fma_f32 v[54:55], v[52:53], v[96:97], v[98:99]
	v_add_f32_dpp v118, v118, v118 quad_perm:[2,3,0,1] row_mask:0xf bank_mask:0xf bound_ctrl:1
	s_nop 0
	ds_read_b128 v[96:99], v90 offset:0x2000
	v_add_f32_dpp v118, v118, v118 row_half_mirror row_mask:0xf bank_mask:0xf bound_ctrl:1
	s_nop 0
	ds_write2_b32 v93, v1, v119 offset0:144 offset1:180
	v_add_f32_dpp v2, v118, v118 row_mirror row_mask:0xf bank_mask:0xf bound_ctrl:1
	v_add_f32_dpp v118, v118, v118 row_mirror row_mask:0xf bank_mask:0xf bound_ctrl:1
	s_nop 0
	s_waitcnt lgkmcnt(4)
	v_permlane16_swap_b32_e32 v118, v2
	v_add_f32_e32 v118, v118, v2
	v_pk_fma_f32 v[52:53], v[102:103], v[118:119], v[54:55] op_sel_hi:[1,0,1]
	v_pk_mul_f32 v[0:1], v[52:53], v[120:121] op_sel_hi:[0,1]
	v_pk_fma_f32 v[0:1], v[52:53], v[122:123], v[0:1] op_sel:[1,0,0]
	v_pk_mul_f32 v[126:127], v[110:111], v[126:127] op_sel_hi:[0,1]
	ds_read_b128 v[120:123], v90 offset:0x6200
	v_add_f32_dpp v0, v0, v0 quad_perm:[1,0,3,2] row_mask:0xf bank_mask:0xf bound_ctrl:1
	v_add_f32_dpp v1, v1, v1 quad_perm:[1,0,3,2] row_mask:0xf bank_mask:0xf bound_ctrl:1
	v_pk_fma_f32 v[54:55], v[52:53], v[124:125], v[126:127]
	v_add_f32_dpp v0, v0, v0 quad_perm:[2,3,0,1] row_mask:0xf bank_mask:0xf bound_ctrl:1
	s_nop 0
	ds_read_b128 v[124:127], v90 offset:0x2200
	v_add_f32_dpp v0, v0, v0 row_half_mirror row_mask:0xf bank_mask:0xf bound_ctrl:1
	s_nop 0
	ds_read2st64_b32 v[108:109], v89 offset0:208 offset1:209
	ds_read2st64_b64 v[100:103], v88 offset0:80 offset1:81
	v_add_f32_dpp v2, v0, v0 row_mirror row_mask:0xf bank_mask:0xf bound_ctrl:1
	v_add_f32_dpp v0, v0, v0 row_mirror row_mask:0xf bank_mask:0xf bound_ctrl:1
	s_nop 0
	s_waitcnt lgkmcnt(7)
	v_permlane16_swap_b32_e32 v0, v2
	v_add_f32_e32 v0, v0, v2
	v_pk_fma_f32 v[52:53], v[104:105], v[0:1], v[54:55] op_sel_hi:[1,0,1]
	v_pk_mul_f32 v[118:119], v[52:53], v[4:5] op_sel_hi:[0,1]
	v_pk_fma_f32 v[118:119], v[52:53], v[6:7], v[118:119] op_sel:[1,0,0]
	v_pk_mul_f32 v[10:11], v[110:111], v[10:11] op_sel:[1,0]
	ds_read_b128 v[4:7], v90 offset:0x6400
	v_add_f32_dpp v118, v118, v118 quad_perm:[1,0,3,2] row_mask:0xf bank_mask:0xf bound_ctrl:1
	v_add_f32_dpp v119, v119, v119 quad_perm:[1,0,3,2] row_mask:0xf bank_mask:0xf bound_ctrl:1
	v_pk_fma_f32 v[54:55], v[52:53], v[8:9], v[10:11]
	v_add_f32_dpp v118, v118, v118 quad_perm:[2,3,0,1] row_mask:0xf bank_mask:0xf bound_ctrl:1
	s_nop 0
	ds_read_b128 v[8:11], v90 offset:0x2400
	v_add_f32_dpp v118, v118, v118 row_half_mirror row_mask:0xf bank_mask:0xf bound_ctrl:1
	s_nop 0
	ds_write2_b32 v93, v1, v119 offset0:216 offset1:252
	v_add_f32_dpp v2, v118, v118 row_mirror row_mask:0xf bank_mask:0xf bound_ctrl:1
	v_add_f32_dpp v118, v118, v118 row_mirror row_mask:0xf bank_mask:0xf bound_ctrl:1
	s_nop 0
	s_waitcnt lgkmcnt(4)
	v_permlane16_swap_b32_e32 v118, v2
	v_add_f32_e32 v118, v118, v2
	v_pk_fma_f32 v[52:53], v[106:107], v[118:119], v[54:55] op_sel_hi:[1,0,1]
	s_cmp_eq_u32 s88, 0x800000
	s_cbranch_scc1 .LBB0_684
	v_pk_mul_f32 v[0:1], v[52:53], v[112:113] op_sel_hi:[0,1]
	v_pk_fma_f32 v[0:1], v[52:53], v[114:115], v[0:1] op_sel:[1,0,0]
	v_pk_mul_f32 v[98:99], v[108:109], v[98:99] op_sel_hi:[0,1]
	ds_read_b128 v[112:115], v90 offset:0x6600
	v_add_f32_dpp v0, v0, v0 quad_perm:[1,0,3,2] row_mask:0xf bank_mask:0xf bound_ctrl:1
	v_add_f32_dpp v1, v1, v1 quad_perm:[1,0,3,2] row_mask:0xf bank_mask:0xf bound_ctrl:1
	v_pk_fma_f32 v[54:55], v[52:53], v[96:97], v[98:99]
	v_add_f32_dpp v0, v0, v0 quad_perm:[2,3,0,1] row_mask:0xf bank_mask:0xf bound_ctrl:1
	s_nop 0
	ds_read_b128 v[96:99], v90 offset:0x2600
	v_add_f32_dpp v0, v0, v0 row_half_mirror row_mask:0xf bank_mask:0xf bound_ctrl:1
	s_nop 0
	ds_read2st64_b32 v[110:111], v89 offset0:210 offset1:211
	ds_read2st64_b64 v[104:107], v88 offset0:82 offset1:83
	v_add_f32_dpp v2, v0, v0 row_mirror row_mask:0xf bank_mask:0xf bound_ctrl:1
	v_add_f32_dpp v0, v0, v0 row_mirror row_mask:0xf bank_mask:0xf bound_ctrl:1
	v_add_u32_e32 v93, 0x480, v93
	s_waitcnt lgkmcnt(7)
	v_permlane16_swap_b32_e32 v0, v2
	v_add_f32_e32 v0, v0, v2
	v_pk_fma_f32 v[52:53], v[100:101], v[0:1], v[54:55] op_sel_hi:[1,0,1]
	v_pk_mul_f32 v[118:119], v[52:53], v[120:121] op_sel_hi:[0,1]
	v_pk_fma_f32 v[118:119], v[52:53], v[122:123], v[118:119] op_sel:[1,0,0]
	v_pk_mul_f32 v[126:127], v[108:109], v[126:127] op_sel:[1,0]
	ds_read_b128 v[120:123], v90 offset:0x6800
	v_add_f32_dpp v118, v118, v118 quad_perm:[1,0,3,2] row_mask:0xf bank_mask:0xf bound_ctrl:1
	v_add_f32_dpp v119, v119, v119 quad_perm:[1,0,3,2] row_mask:0xf bank_mask:0xf bound_ctrl:1
	v_pk_fma_f32 v[54:55], v[52:53], v[124:125], v[126:127]
	v_add_f32_dpp v118, v118, v118 quad_perm:[2,3,0,1] row_mask:0xf bank_mask:0xf bound_ctrl:1
	s_nop 0
	ds_read_b128 v[124:127], v90 offset:0x2800
	v_add_f32_dpp v118, v118, v118 row_half_mirror row_mask:0xf bank_mask:0xf bound_ctrl:1
	s_nop 0
	ds_write2_b32 v93, v1, v119 offset0:0 offset1:36
	v_add_f32_dpp v2, v118, v118 row_mirror row_mask:0xf bank_mask:0xf bound_ctrl:1
	v_add_f32_dpp v118, v118, v118 row_mirror row_mask:0xf bank_mask:0xf bound_ctrl:1
	s_nop 0
	s_waitcnt lgkmcnt(4)
	v_permlane16_swap_b32_e32 v118, v2
	v_add_f32_e32 v118, v118, v2
	v_pk_fma_f32 v[52:53], v[102:103], v[118:119], v[54:55] op_sel_hi:[1,0,1]
	v_pk_mul_f32 v[0:1], v[52:53], v[4:5] op_sel_hi:[0,1]
	v_pk_fma_f32 v[0:1], v[52:53], v[6:7], v[0:1] op_sel:[1,0,0]
	v_pk_mul_f32 v[10:11], v[110:111], v[10:11] op_sel_hi:[0,1]
	ds_read_b128 v[4:7], v90 offset:0x6a00
	v_add_f32_dpp v0, v0, v0 quad_perm:[1,0,3,2] row_mask:0xf bank_mask:0xf bound_ctrl:1
	v_add_f32_dpp v1, v1, v1 quad_perm:[1,0,3,2] row_mask:0xf bank_mask:0xf bound_ctrl:1
	v_pk_fma_f32 v[54:55], v[52:53], v[8:9], v[10:11]
	v_add_f32_dpp v0, v0, v0 quad_perm:[2,3,0,1] row_mask:0xf bank_mask:0xf bound_ctrl:1
	s_nop 0
	ds_read_b128 v[8:11], v90 offset:0x2a00
	v_add_f32_dpp v0, v0, v0 row_half_mirror row_mask:0xf bank_mask:0xf bound_ctrl:1
	s_nop 0
	ds_read2st64_b32 v[108:109], v89 offset0:212 offset1:213
	ds_read2st64_b64 v[100:103], v88 offset0:84 offset1:85
	v_add_f32_dpp v2, v0, v0 row_mirror row_mask:0xf bank_mask:0xf bound_ctrl:1
	v_add_f32_dpp v0, v0, v0 row_mirror row_mask:0xf bank_mask:0xf bound_ctrl:1
	s_nop 0
	s_waitcnt lgkmcnt(7)
	v_permlane16_swap_b32_e32 v0, v2
	v_add_f32_e32 v0, v0, v2
	v_pk_fma_f32 v[52:53], v[104:105], v[0:1], v[54:55] op_sel_hi:[1,0,1]
	v_pk_mul_f32 v[118:119], v[52:53], v[112:113] op_sel_hi:[0,1]
	v_pk_fma_f32 v[118:119], v[52:53], v[114:115], v[118:119] op_sel:[1,0,0]
	v_pk_mul_f32 v[98:99], v[110:111], v[98:99] op_sel:[1,0]
	ds_read_b128 v[112:115], v90 offset:0x6c00
	v_add_f32_dpp v118, v118, v118 quad_perm:[1,0,3,2] row_mask:0xf bank_mask:0xf bound_ctrl:1
	v_add_f32_dpp v119, v119, v119 quad_perm:[1,0,3,2] row_mask:0xf bank_mask:0xf bound_ctrl:1
	v_pk_fma_f32 v[54:55], v[52:53], v[96:97], v[98:99]
	v_add_f32_dpp v118, v118, v118 quad_perm:[2,3,0,1] row_mask:0xf bank_mask:0xf bound_ctrl:1
	s_nop 0
	ds_read_b128 v[96:99], v90 offset:0x2c00
	v_add_f32_dpp v118, v118, v118 row_half_mirror row_mask:0xf bank_mask:0xf bound_ctrl:1
	s_nop 0
	ds_write2_b32 v93, v1, v119 offset0:72 offset1:108
	v_add_f32_dpp v2, v118, v118 row_mirror row_mask:0xf bank_mask:0xf bound_ctrl:1
	v_add_f32_dpp v118, v118, v118 row_mirror row_mask:0xf bank_mask:0xf bound_ctrl:1
	s_nop 0
	s_waitcnt lgkmcnt(4)
	v_permlane16_swap_b32_e32 v118, v2
	v_add_f32_e32 v118, v118, v2
	v_pk_fma_f32 v[52:53], v[106:107], v[118:119], v[54:55] op_sel_hi:[1,0,1]
	v_pk_mul_f32 v[0:1], v[52:53], v[120:121] op_sel_hi:[0,1]
	v_pk_fma_f32 v[0:1], v[52:53], v[122:123], v[0:1] op_sel:[1,0,0]
	v_pk_mul_f32 v[126:127], v[108:109], v[126:127] op_sel_hi:[0,1]
	ds_read_b128 v[120:123], v90 offset:0x6e00
	v_add_f32_dpp v0, v0, v0 quad_perm:[1,0,3,2] row_mask:0xf bank_mask:0xf bound_ctrl:1
	v_add_f32_dpp v1, v1, v1 quad_perm:[1,0,3,2] row_mask:0xf bank_mask:0xf bound_ctrl:1
	v_pk_fma_f32 v[54:55], v[52:53], v[124:125], v[126:127]
	v_add_f32_dpp v0, v0, v0 quad_perm:[2,3,0,1] row_mask:0xf bank_mask:0xf bound_ctrl:1
	s_nop 0
	ds_read_b128 v[124:127], v90 offset:0x2e00
	v_add_f32_dpp v0, v0, v0 row_half_mirror row_mask:0xf bank_mask:0xf bound_ctrl:1
	s_nop 0
	ds_read2st64_b32 v[110:111], v89 offset0:214 offset1:215
	ds_read2st64_b64 v[104:107], v88 offset0:86 offset1:87
	v_add_f32_dpp v2, v0, v0 row_mirror row_mask:0xf bank_mask:0xf bound_ctrl:1
	v_add_f32_dpp v0, v0, v0 row_mirror row_mask:0xf bank_mask:0xf bound_ctrl:1
	s_nop 0
	s_waitcnt lgkmcnt(7)
	v_permlane16_swap_b32_e32 v0, v2
	v_add_f32_e32 v0, v0, v2
	v_pk_fma_f32 v[52:53], v[100:101], v[0:1], v[54:55] op_sel_hi:[1,0,1]
	v_pk_mul_f32 v[118:119], v[52:53], v[4:5] op_sel_hi:[0,1]
	v_pk_fma_f32 v[118:119], v[52:53], v[6:7], v[118:119] op_sel:[1,0,0]
	v_pk_mul_f32 v[10:11], v[108:109], v[10:11] op_sel:[1,0]
	ds_read_b128 v[4:7], v90 offset:0x7000
	v_add_f32_dpp v118, v118, v118 quad_perm:[1,0,3,2] row_mask:0xf bank_mask:0xf bound_ctrl:1
	v_add_f32_dpp v119, v119, v119 quad_perm:[1,0,3,2] row_mask:0xf bank_mask:0xf bound_ctrl:1
	v_pk_fma_f32 v[54:55], v[52:53], v[8:9], v[10:11]
	v_add_f32_dpp v118, v118, v118 quad_perm:[2,3,0,1] row_mask:0xf bank_mask:0xf bound_ctrl:1
	s_nop 0
	ds_read_b128 v[8:11], v90 offset:0x3000
	v_add_f32_dpp v118, v118, v118 row_half_mirror row_mask:0xf bank_mask:0xf bound_ctrl:1
	s_nop 0
	ds_write2_b32 v93, v1, v119 offset0:144 offset1:180
	v_add_f32_dpp v2, v118, v118 row_mirror row_mask:0xf bank_mask:0xf bound_ctrl:1
	v_add_f32_dpp v118, v118, v118 row_mirror row_mask:0xf bank_mask:0xf bound_ctrl:1
	s_nop 0
	s_waitcnt lgkmcnt(4)
	v_permlane16_swap_b32_e32 v118, v2
	v_add_f32_e32 v118, v118, v2
	v_pk_fma_f32 v[52:53], v[102:103], v[118:119], v[54:55] op_sel_hi:[1,0,1]
	v_pk_mul_f32 v[0:1], v[52:53], v[112:113] op_sel_hi:[0,1]
	v_pk_fma_f32 v[0:1], v[52:53], v[114:115], v[0:1] op_sel:[1,0,0]
	v_pk_mul_f32 v[98:99], v[110:111], v[98:99] op_sel_hi:[0,1]
	ds_read_b128 v[112:115], v90 offset:0x7200
	v_add_f32_dpp v0, v0, v0 quad_perm:[1,0,3,2] row_mask:0xf bank_mask:0xf bound_ctrl:1
	v_add_f32_dpp v1, v1, v1 quad_perm:[1,0,3,2] row_mask:0xf bank_mask:0xf bound_ctrl:1
	v_pk_fma_f32 v[54:55], v[52:53], v[96:97], v[98:99]
	v_add_f32_dpp v0, v0, v0 quad_perm:[2,3,0,1] row_mask:0xf bank_mask:0xf bound_ctrl:1
	s_nop 0
	ds_read_b128 v[96:99], v90 offset:0x3200
	v_add_f32_dpp v0, v0, v0 row_half_mirror row_mask:0xf bank_mask:0xf bound_ctrl:1
	s_nop 0
	ds_read2st64_b32 v[108:109], v89 offset0:216 offset1:217
	ds_read2st64_b64 v[100:103], v88 offset0:88 offset1:89
	v_add_f32_dpp v2, v0, v0 row_mirror row_mask:0xf bank_mask:0xf bound_ctrl:1
	v_add_f32_dpp v0, v0, v0 row_mirror row_mask:0xf bank_mask:0xf bound_ctrl:1
	s_nop 0
	s_waitcnt lgkmcnt(7)
	v_permlane16_swap_b32_e32 v0, v2
	v_add_f32_e32 v0, v0, v2
	v_pk_fma_f32 v[52:53], v[104:105], v[0:1], v[54:55] op_sel_hi:[1,0,1]
	v_pk_mul_f32 v[118:119], v[52:53], v[120:121] op_sel_hi:[0,1]
	v_pk_fma_f32 v[118:119], v[52:53], v[122:123], v[118:119] op_sel:[1,0,0]
	v_pk_mul_f32 v[126:127], v[110:111], v[126:127] op_sel:[1,0]
	ds_read_b128 v[120:123], v90 offset:0x7400
	v_add_f32_dpp v118, v118, v118 quad_perm:[1,0,3,2] row_mask:0xf bank_mask:0xf bound_ctrl:1
	v_add_f32_dpp v119, v119, v119 quad_perm:[1,0,3,2] row_mask:0xf bank_mask:0xf bound_ctrl:1
	v_pk_fma_f32 v[54:55], v[52:53], v[124:125], v[126:127]
	v_add_f32_dpp v118, v118, v118 quad_perm:[2,3,0,1] row_mask:0xf bank_mask:0xf bound_ctrl:1
	s_nop 0
	ds_read_b128 v[124:127], v90 offset:0x3400
	v_add_f32_dpp v118, v118, v118 row_half_mirror row_mask:0xf bank_mask:0xf bound_ctrl:1
	s_nop 0
	ds_write2_b32 v93, v1, v119 offset0:216 offset1:252
	v_add_f32_dpp v2, v118, v118 row_mirror row_mask:0xf bank_mask:0xf bound_ctrl:1
	v_add_f32_dpp v118, v118, v118 row_mirror row_mask:0xf bank_mask:0xf bound_ctrl:1
	s_nop 0
	s_waitcnt lgkmcnt(4)
	v_permlane16_swap_b32_e32 v118, v2
	v_add_f32_e32 v118, v118, v2
	v_pk_fma_f32 v[52:53], v[106:107], v[118:119], v[54:55] op_sel_hi:[1,0,1]
	v_pk_mul_f32 v[0:1], v[52:53], v[4:5] op_sel_hi:[0,1]
	v_pk_fma_f32 v[0:1], v[52:53], v[6:7], v[0:1] op_sel:[1,0,0]
	v_pk_mul_f32 v[10:11], v[108:109], v[10:11] op_sel_hi:[0,1]
	ds_read_b128 v[4:7], v90 offset:0x7600
	v_add_f32_dpp v0, v0, v0 quad_perm:[1,0,3,2] row_mask:0xf bank_mask:0xf bound_ctrl:1
	v_add_f32_dpp v1, v1, v1 quad_perm:[1,0,3,2] row_mask:0xf bank_mask:0xf bound_ctrl:1
	v_pk_fma_f32 v[54:55], v[52:53], v[8:9], v[10:11]
	v_add_f32_dpp v0, v0, v0 quad_perm:[2,3,0,1] row_mask:0xf bank_mask:0xf bound_ctrl:1
	s_nop 0
	ds_read_b128 v[8:11], v90 offset:0x3600
	v_add_f32_dpp v0, v0, v0 row_half_mirror row_mask:0xf bank_mask:0xf bound_ctrl:1
	s_nop 0
	ds_read2st64_b32 v[110:111], v89 offset0:218 offset1:219
	ds_read2st64_b64 v[104:107], v88 offset0:90 offset1:91
	v_add_f32_dpp v2, v0, v0 row_mirror row_mask:0xf bank_mask:0xf bound_ctrl:1
	v_add_f32_dpp v0, v0, v0 row_mirror row_mask:0xf bank_mask:0xf bound_ctrl:1
	v_add_u32_e32 v93, 0x480, v93
	s_waitcnt lgkmcnt(7)
	v_permlane16_swap_b32_e32 v0, v2
	v_add_f32_e32 v0, v0, v2
	v_pk_fma_f32 v[52:53], v[100:101], v[0:1], v[54:55] op_sel_hi:[1,0,1]
	v_pk_mul_f32 v[118:119], v[52:53], v[112:113] op_sel_hi:[0,1]
	v_pk_fma_f32 v[118:119], v[52:53], v[114:115], v[118:119] op_sel:[1,0,0]
	v_pk_mul_f32 v[98:99], v[108:109], v[98:99] op_sel:[1,0]
	ds_read_b128 v[112:115], v90 offset:0x7800
	v_add_f32_dpp v118, v118, v118 quad_perm:[1,0,3,2] row_mask:0xf bank_mask:0xf bound_ctrl:1
	v_add_f32_dpp v119, v119, v119 quad_perm:[1,0,3,2] row_mask:0xf bank_mask:0xf bound_ctrl:1
	v_pk_fma_f32 v[54:55], v[52:53], v[96:97], v[98:99]
	v_add_f32_dpp v118, v118, v118 quad_perm:[2,3,0,1] row_mask:0xf bank_mask:0xf bound_ctrl:1
	s_nop 0
	ds_read_b128 v[96:99], v90 offset:0x3800
	v_add_f32_dpp v118, v118, v118 row_half_mirror row_mask:0xf bank_mask:0xf bound_ctrl:1
	s_nop 0
	ds_write2_b32 v93, v1, v119 offset0:0 offset1:36
	v_add_f32_dpp v2, v118, v118 row_mirror row_mask:0xf bank_mask:0xf bound_ctrl:1
	v_add_f32_dpp v118, v118, v118 row_mirror row_mask:0xf bank_mask:0xf bound_ctrl:1
	s_nop 0
	s_waitcnt lgkmcnt(4)
	v_permlane16_swap_b32_e32 v118, v2
	v_add_f32_e32 v118, v118, v2
	v_pk_fma_f32 v[52:53], v[102:103], v[118:119], v[54:55] op_sel_hi:[1,0,1]
	v_pk_mul_f32 v[0:1], v[52:53], v[120:121] op_sel_hi:[0,1]
	v_pk_fma_f32 v[0:1], v[52:53], v[122:123], v[0:1] op_sel:[1,0,0]
	v_pk_mul_f32 v[126:127], v[110:111], v[126:127] op_sel_hi:[0,1]
	ds_read_b128 v[120:123], v90 offset:0x7a00
	v_add_f32_dpp v0, v0, v0 quad_perm:[1,0,3,2] row_mask:0xf bank_mask:0xf bound_ctrl:1
	v_add_f32_dpp v1, v1, v1 quad_perm:[1,0,3,2] row_mask:0xf bank_mask:0xf bound_ctrl:1
	v_pk_fma_f32 v[54:55], v[52:53], v[124:125], v[126:127]
	v_add_f32_dpp v0, v0, v0 quad_perm:[2,3,0,1] row_mask:0xf bank_mask:0xf bound_ctrl:1
	s_nop 0
	ds_read_b128 v[124:127], v90 offset:0x3a00
	v_add_f32_dpp v0, v0, v0 row_half_mirror row_mask:0xf bank_mask:0xf bound_ctrl:1
	s_nop 0
	ds_read2st64_b32 v[108:109], v89 offset0:220 offset1:221
	ds_read2st64_b64 v[100:103], v88 offset0:92 offset1:93
	v_add_f32_dpp v2, v0, v0 row_mirror row_mask:0xf bank_mask:0xf bound_ctrl:1
	v_add_f32_dpp v0, v0, v0 row_mirror row_mask:0xf bank_mask:0xf bound_ctrl:1
	s_nop 0
	s_waitcnt lgkmcnt(7)
	v_permlane16_swap_b32_e32 v0, v2
	v_add_f32_e32 v0, v0, v2
	v_pk_fma_f32 v[52:53], v[104:105], v[0:1], v[54:55] op_sel_hi:[1,0,1]
	v_pk_mul_f32 v[118:119], v[52:53], v[4:5] op_sel_hi:[0,1]
	v_pk_fma_f32 v[118:119], v[52:53], v[6:7], v[118:119] op_sel:[1,0,0]
	v_pk_mul_f32 v[10:11], v[110:111], v[10:11] op_sel:[1,0]
	ds_read_b128 v[4:7], v90 offset:0x7c00
	v_add_f32_dpp v118, v118, v118 quad_perm:[1,0,3,2] row_mask:0xf bank_mask:0xf bound_ctrl:1
	v_add_f32_dpp v119, v119, v119 quad_perm:[1,0,3,2] row_mask:0xf bank_mask:0xf bound_ctrl:1
	v_pk_fma_f32 v[54:55], v[52:53], v[8:9], v[10:11]
	v_add_f32_dpp v118, v118, v118 quad_perm:[2,3,0,1] row_mask:0xf bank_mask:0xf bound_ctrl:1
	s_nop 0
	ds_read_b128 v[8:11], v90 offset:0x3c00
	v_add_f32_dpp v118, v118, v118 row_half_mirror row_mask:0xf bank_mask:0xf bound_ctrl:1
	s_nop 0
	ds_write2_b32 v93, v1, v119 offset0:72 offset1:108
	v_add_f32_dpp v2, v118, v118 row_mirror row_mask:0xf bank_mask:0xf bound_ctrl:1
	v_add_f32_dpp v118, v118, v118 row_mirror row_mask:0xf bank_mask:0xf bound_ctrl:1
	s_nop 0
	s_waitcnt lgkmcnt(4)
	v_permlane16_swap_b32_e32 v118, v2
	v_add_f32_e32 v118, v118, v2
	v_pk_fma_f32 v[52:53], v[106:107], v[118:119], v[54:55] op_sel_hi:[1,0,1]
	v_pk_mul_f32 v[0:1], v[52:53], v[112:113] op_sel_hi:[0,1]
	v_pk_fma_f32 v[0:1], v[52:53], v[114:115], v[0:1] op_sel:[1,0,0]
	v_pk_mul_f32 v[98:99], v[108:109], v[98:99] op_sel_hi:[0,1]
	ds_read_b128 v[112:115], v90 offset:0x7e00
	v_add_f32_dpp v0, v0, v0 quad_perm:[1,0,3,2] row_mask:0xf bank_mask:0xf bound_ctrl:1
	v_add_f32_dpp v1, v1, v1 quad_perm:[1,0,3,2] row_mask:0xf bank_mask:0xf bound_ctrl:1
	v_pk_fma_f32 v[54:55], v[52:53], v[96:97], v[98:99]
	v_add_f32_dpp v0, v0, v0 quad_perm:[2,3,0,1] row_mask:0xf bank_mask:0xf bound_ctrl:1
	s_nop 0
	ds_read_b128 v[96:99], v90 offset:0x3e00
	v_add_f32_dpp v0, v0, v0 row_half_mirror row_mask:0xf bank_mask:0xf bound_ctrl:1
	s_nop 0
	ds_read2st64_b32 v[110:111], v89 offset0:222 offset1:223
	ds_read2st64_b64 v[104:107], v88 offset0:94 offset1:95
	v_add_f32_dpp v2, v0, v0 row_mirror row_mask:0xf bank_mask:0xf bound_ctrl:1
	v_add_f32_dpp v0, v0, v0 row_mirror row_mask:0xf bank_mask:0xf bound_ctrl:1
	s_nop 0
	s_waitcnt lgkmcnt(7)
	v_permlane16_swap_b32_e32 v0, v2
	v_add_f32_e32 v0, v0, v2
	v_pk_fma_f32 v[52:53], v[100:101], v[0:1], v[54:55] op_sel_hi:[1,0,1]
	v_pk_mul_f32 v[118:119], v[52:53], v[120:121] op_sel_hi:[0,1]
	v_pk_fma_f32 v[118:119], v[52:53], v[122:123], v[118:119] op_sel:[1,0,0]
	v_pk_mul_f32 v[126:127], v[108:109], v[126:127] op_sel:[1,0]
	s_nop 0
	v_add_f32_dpp v118, v118, v118 quad_perm:[1,0,3,2] row_mask:0xf bank_mask:0xf bound_ctrl:1
	v_add_f32_dpp v119, v119, v119 quad_perm:[1,0,3,2] row_mask:0xf bank_mask:0xf bound_ctrl:1
	v_pk_fma_f32 v[54:55], v[52:53], v[124:125], v[126:127]
	v_add_f32_dpp v118, v118, v118 quad_perm:[2,3,0,1] row_mask:0xf bank_mask:0xf bound_ctrl:1
	s_nop 0
	s_nop 0
	v_add_f32_dpp v118, v118, v118 row_half_mirror row_mask:0xf bank_mask:0xf bound_ctrl:1
	s_nop 0
	ds_write2_b32 v93, v1, v119 offset0:144 offset1:180
	v_add_f32_dpp v2, v118, v118 row_mirror row_mask:0xf bank_mask:0xf bound_ctrl:1
	v_add_f32_dpp v118, v118, v118 row_mirror row_mask:0xf bank_mask:0xf bound_ctrl:1
	s_nop 0
	s_waitcnt lgkmcnt(2)
	v_permlane16_swap_b32_e32 v118, v2
	v_add_f32_e32 v118, v118, v2
	v_pk_fma_f32 v[52:53], v[102:103], v[118:119], v[54:55] op_sel_hi:[1,0,1]
	v_pk_mul_f32 v[0:1], v[52:53], v[4:5] op_sel_hi:[0,1]
	v_pk_fma_f32 v[0:1], v[52:53], v[6:7], v[0:1] op_sel:[1,0,0]
	v_pk_mul_f32 v[10:11], v[110:111], v[10:11] op_sel_hi:[0,1]
	s_nop 0
	v_add_f32_dpp v0, v0, v0 quad_perm:[1,0,3,2] row_mask:0xf bank_mask:0xf bound_ctrl:1
	v_add_f32_dpp v1, v1, v1 quad_perm:[1,0,3,2] row_mask:0xf bank_mask:0xf bound_ctrl:1
	v_pk_fma_f32 v[54:55], v[52:53], v[8:9], v[10:11]
	v_add_f32_dpp v0, v0, v0 quad_perm:[2,3,0,1] row_mask:0xf bank_mask:0xf bound_ctrl:1
	s_nop 0
	s_nop 0
	v_add_f32_dpp v0, v0, v0 row_half_mirror row_mask:0xf bank_mask:0xf bound_ctrl:1
	s_nop 0
	s_nop 0
	v_add_f32_dpp v2, v0, v0 row_mirror row_mask:0xf bank_mask:0xf bound_ctrl:1
	v_add_f32_dpp v0, v0, v0 row_mirror row_mask:0xf bank_mask:0xf bound_ctrl:1
	s_nop 0
	s_waitcnt lgkmcnt(1)
	v_permlane16_swap_b32_e32 v0, v2
	v_add_f32_e32 v0, v0, v2
	v_pk_fma_f32 v[52:53], v[104:105], v[0:1], v[54:55] op_sel_hi:[1,0,1]
	v_pk_mul_f32 v[118:119], v[52:53], v[112:113] op_sel_hi:[0,1]
	v_pk_fma_f32 v[118:119], v[52:53], v[114:115], v[118:119] op_sel:[1,0,0]
	v_pk_mul_f32 v[98:99], v[110:111], v[98:99] op_sel:[1,0]
	s_nop 0
	v_add_f32_dpp v118, v118, v118 quad_perm:[1,0,3,2] row_mask:0xf bank_mask:0xf bound_ctrl:1
	v_add_f32_dpp v119, v119, v119 quad_perm:[1,0,3,2] row_mask:0xf bank_mask:0xf bound_ctrl:1
	v_pk_fma_f32 v[54:55], v[52:53], v[96:97], v[98:99]
	v_add_f32_dpp v118, v118, v118 quad_perm:[2,3,0,1] row_mask:0xf bank_mask:0xf bound_ctrl:1
	s_nop 0
	s_nop 0
	v_add_f32_dpp v118, v118, v118 row_half_mirror row_mask:0xf bank_mask:0xf bound_ctrl:1
	s_nop 0
	ds_write2_b32 v93, v1, v119 offset0:216 offset1:252
	v_add_f32_dpp v2, v118, v118 row_mirror row_mask:0xf bank_mask:0xf bound_ctrl:1
	v_add_f32_dpp v118, v118, v118 row_mirror row_mask:0xf bank_mask:0xf bound_ctrl:1
	s_nop 0
	s_nop 0
	v_permlane16_swap_b32_e32 v118, v2
	v_add_f32_e32 v118, v118, v2
	v_pk_fma_f32 v[52:53], v[106:107], v[118:119], v[54:55] op_sel_hi:[1,0,1]
